# adaLN table build rewritten by hand in P4 and P7 thin phases (loads batched, hidden under the grid barrier)
# baseline (speedup 1.0000x reference)
.LBB0_769:
	s_lshl_b64 s[0:1], s[78:79], 2
	v_readlane_b32 s72, v253, 7
	s_add_i32 s9, s49, 1
	v_readlane_b32 s78, v253, 13
	s_waitcnt vmcnt(0)
	v_readlane_b32 s79, v253, 14
	v_readlane_b32 s80, v253, 15
	v_readlane_b32 s81, v253, 16
	s_add_u32 s0, s78, s0
	v_readlane_b32 s82, v253, 17
	v_readlane_b32 s83, v253, 18
	s_addc_u32 s1, s79, s1
	v_readlane_b32 s50, v252, 52
	v_readlane_b32 s80, v252, 48
	v_readlane_b32 s56, v252, 55
	s_cmp_eq_u32 s49, 3
	s_mov_b64 s[36:37], -1
	v_readlane_b32 s51, v252, 53
	v_readlane_b32 s81, v252, 49
	v_readlane_b32 s82, v252, 50
	v_readlane_b32 s83, v252, 51
	v_readlane_b32 s57, v252, 56
	s_barrier
	v_readlane_b32 s73, v253, 8
	v_readlane_b32 s74, v253, 9
	v_readlane_b32 s75, v253, 10
	v_readlane_b32 s76, v253, 11
	v_readlane_b32 s77, v253, 12
	v_readlane_b32 s84, v253, 19
	v_readlane_b32 s85, v253, 20
	v_readlane_b32 s86, v253, 21
	v_readlane_b32 s87, v253, 22
	s_cbranch_scc1 .LBB0_812
	v_mov_b32_e32 v1, v0
	s_waitcnt vmcnt(0)
	s_waitcnt vmcnt(0)
	v_readfirstlane_b32 s23, v1
	s_cmp_lt_u32 s23, 64
	s_barrier
	s_cbranch_scc1 .LBB0_800
	s_lshl_b32 s64, s9, 11
	s_lshl_b64 s[12:13], s[64:65], 2
	v_readlane_b32 s72, v253, 7
	v_readlane_b32 s73, v253, 8
	s_add_u32 s36, s72, s12
	s_mul_i32 s64, s49, 3
	s_movk_i32 s12, 0x1840
	s_addc_u32 s37, s73, s13
	s_add_i32 s58, s64, 3
	s_mov_b32 s59, s65
	v_cmp_gt_i32_e32 vcc, s12, v1
	v_lshl_add_u32 v2, v1, 2, 0
	v_readlane_b32 s74, v253, 9
	v_readlane_b32 s75, v253, 10
	v_readlane_b32 s76, v253, 11
	v_readlane_b32 s77, v253, 12
	v_readlane_b32 s78, v253, 13
	v_readlane_b32 s79, v253, 14
	v_readlane_b32 s80, v253, 15
	v_readlane_b32 s81, v253, 16
	v_readlane_b32 s82, v253, 17
	v_readlane_b32 s83, v253, 18
	v_readlane_b32 s84, v253, 19
	v_readlane_b32 s85, v253, 20
	v_readlane_b32 s86, v253, 21
	v_readlane_b32 s87, v253, 22
	v_readlane_b32 s80, v252, 48
	v_readlane_b32 s81, v252, 49
	v_readlane_b32 s82, v252, 50
	v_readlane_b32 s83, v252, 51
	s_mul_i32 s12, s64, 0xc000
	s_add_u32 s12, s50, s12
	s_addc_u32 s13, s51, 0
	s_add_u32 s16, s12, 0xa000
	s_addc_u32 s17, s13, 0
	s_add_u32 s12, s12, 0x24000
	s_addc_u32 s13, s13, 0
	s_add_u32 s72, s12, 0x2000
	s_addc_u32 s73, s13, 0
	s_mov_b64 s[68:69], exec
	v_subrev_u32_e32 v4, 64, v1
	v_add_u32_e32 v5, 0xffffff00, v2
	v_add_u32_e32 v6, 0xc000, v5
	s_mov_b32 s58, 0xc000
	v_mov_b32_e32 v8, v4
	v_lshrrev_b32_e32 v9, 11, v8
	v_and_b32_e32 v8, 0x7ff, v8
	v_lshlrev_b32_e32 v8, 2, v8
	v_mad_u32_u24 v9, v9, s58, v8
	global_load_dword v10, v9, s[16:17]
	global_load_dword v11, v8, s[0:1]
	global_load_dword v12, v8, s[36:37]
	global_load_dword v13, v9, s[72:73]
	global_load_dword v14, v9, s[12:13]
	v_add_u32_e32 v16, 448, v4
	v_lshrrev_b32_e32 v17, 11, v16
	v_and_b32_e32 v16, 0x7ff, v16
	v_lshlrev_b32_e32 v16, 2, v16
	v_mad_u32_u24 v17, v17, s58, v16
	global_load_dword v18, v17, s[16:17]
	global_load_dword v19, v16, s[0:1]
	global_load_dword v20, v16, s[36:37]
	global_load_dword v21, v17, s[72:73]
	global_load_dword v22, v17, s[12:13]
	v_add_u32_e32 v24, 896, v4
	v_lshrrev_b32_e32 v25, 11, v24
	v_and_b32_e32 v24, 0x7ff, v24
	v_lshlrev_b32_e32 v24, 2, v24
	v_mad_u32_u24 v25, v25, s58, v24
	global_load_dword v26, v25, s[16:17]
	global_load_dword v27, v24, s[0:1]
	global_load_dword v28, v24, s[36:37]
	global_load_dword v29, v25, s[72:73]
	global_load_dword v30, v25, s[12:13]
	v_add_u32_e32 v32, 1344, v4
	v_lshrrev_b32_e32 v33, 11, v32
	v_and_b32_e32 v32, 0x7ff, v32
	v_lshlrev_b32_e32 v32, 2, v32
	v_mad_u32_u24 v33, v33, s58, v32
	global_load_dword v34, v33, s[16:17]
	global_load_dword v35, v32, s[0:1]
	global_load_dword v36, v32, s[36:37]
	global_load_dword v37, v33, s[72:73]
	global_load_dword v38, v33, s[12:13]
	v_add_u32_e32 v40, 1792, v4
	v_lshrrev_b32_e32 v41, 11, v40
	v_and_b32_e32 v40, 0x7ff, v40
	v_lshlrev_b32_e32 v40, 2, v40
	v_mad_u32_u24 v41, v41, s58, v40
	global_load_dword v42, v41, s[16:17]
	global_load_dword v43, v40, s[0:1]
	global_load_dword v44, v40, s[36:37]
	global_load_dword v45, v41, s[72:73]
	global_load_dword v46, v41, s[12:13]
	v_add_u32_e32 v48, 2240, v4
	v_lshrrev_b32_e32 v49, 11, v48
	v_and_b32_e32 v48, 0x7ff, v48
	v_lshlrev_b32_e32 v48, 2, v48
	v_mad_u32_u24 v49, v49, s58, v48
	global_load_dword v50, v49, s[16:17]
	global_load_dword v51, v48, s[0:1]
	global_load_dword v52, v48, s[36:37]
	global_load_dword v53, v49, s[72:73]
	global_load_dword v54, v49, s[12:13]
	v_add_u32_e32 v56, 2688, v4
	v_lshrrev_b32_e32 v57, 11, v56
	v_and_b32_e32 v56, 0x7ff, v56
	v_lshlrev_b32_e32 v56, 2, v56
	v_mad_u32_u24 v57, v57, s58, v56
	global_load_dword v58, v57, s[16:17]
	global_load_dword v59, v56, s[0:1]
	global_load_dword v60, v56, s[36:37]
	global_load_dword v61, v57, s[72:73]
	global_load_dword v62, v57, s[12:13]
	v_add_u32_e32 v64, 3136, v4
	v_lshrrev_b32_e32 v65, 11, v64
	v_and_b32_e32 v64, 0x7ff, v64
	v_lshlrev_b32_e32 v64, 2, v64
	v_mad_u32_u24 v65, v65, s58, v64
	global_load_dword v66, v65, s[16:17]
	global_load_dword v67, v64, s[0:1]
	global_load_dword v68, v64, s[36:37]
	global_load_dword v69, v65, s[72:73]
	global_load_dword v70, v65, s[12:13]
	v_add_u32_e32 v72, 3584, v4
	v_lshrrev_b32_e32 v73, 11, v72
	v_and_b32_e32 v72, 0x7ff, v72
	v_lshlrev_b32_e32 v72, 2, v72
	v_mad_u32_u24 v73, v73, s58, v72
	global_load_dword v74, v73, s[16:17]
	global_load_dword v75, v72, s[0:1]
	global_load_dword v76, v72, s[36:37]
	global_load_dword v77, v73, s[72:73]
	global_load_dword v78, v73, s[12:13]
	v_add_u32_e32 v80, 4032, v4
	v_lshrrev_b32_e32 v81, 11, v80
	v_and_b32_e32 v80, 0x7ff, v80
	v_lshlrev_b32_e32 v80, 2, v80
	v_mad_u32_u24 v81, v81, s58, v80
	global_load_dword v82, v81, s[16:17]
	global_load_dword v83, v80, s[0:1]
	global_load_dword v84, v80, s[36:37]
	global_load_dword v85, v81, s[72:73]
	global_load_dword v86, v81, s[12:13]
	v_add_u32_e32 v88, 4480, v4
	v_lshrrev_b32_e32 v89, 11, v88
	v_and_b32_e32 v88, 0x7ff, v88
	v_lshlrev_b32_e32 v88, 2, v88
	v_mad_u32_u24 v89, v89, s58, v88
	global_load_dword v90, v89, s[16:17]
	global_load_dword v91, v88, s[0:1]
	global_load_dword v92, v88, s[36:37]
	global_load_dword v93, v89, s[72:73]
	global_load_dword v94, v89, s[12:13]
	v_add_u32_e32 v96, 4928, v4
	v_lshrrev_b32_e32 v97, 11, v96
	v_and_b32_e32 v96, 0x7ff, v96
	v_lshlrev_b32_e32 v96, 2, v96
	v_mad_u32_u24 v97, v97, s58, v96
	global_load_dword v98, v97, s[16:17]
	global_load_dword v99, v96, s[0:1]
	global_load_dword v100, v96, s[36:37]
	global_load_dword v101, v97, s[72:73]
	global_load_dword v102, v97, s[12:13]
	s_waitcnt vmcnt(55)
	v_mul_f32_e32 v10, v10, v11
	v_add_f32_e32 v13, 1.0, v13
	v_mul_f32_e32 v13, v12, v13
	ds_write_b32 v5, v10 offset:0
	ds_write_b32 v5, v13 offset:24576
	ds_write_b32 v6, v14 offset:0
	v_add_u32_e32 v104, 5376, v4
	v_lshrrev_b32_e32 v105, 11, v104
	v_and_b32_e32 v104, 0x7ff, v104
	v_lshlrev_b32_e32 v104, 2, v104
	v_mad_u32_u24 v105, v105, s58, v104
	global_load_dword v106, v105, s[16:17]
	global_load_dword v107, v104, s[0:1]
	global_load_dword v108, v104, s[36:37]
	global_load_dword v109, v105, s[72:73]
	global_load_dword v110, v105, s[12:13]
	s_waitcnt vmcnt(55)
	v_mul_f32_e32 v18, v18, v19
	v_add_f32_e32 v21, 1.0, v21
	v_mul_f32_e32 v21, v20, v21
	ds_write_b32 v5, v18 offset:1792
	ds_write_b32 v5, v21 offset:26368
	ds_write_b32 v6, v22 offset:1792
	v_add_u32_e32 v112, 5824, v4
	v_lshrrev_b32_e32 v113, 11, v112
	v_and_b32_e32 v112, 0x7ff, v112
	v_lshlrev_b32_e32 v112, 2, v112
	v_mad_u32_u24 v113, v113, s58, v112
	global_load_dword v114, v113, s[16:17]
	global_load_dword v115, v112, s[0:1]
	global_load_dword v116, v112, s[36:37]
	global_load_dword v117, v113, s[72:73]
	global_load_dword v118, v113, s[12:13]
	s_waitcnt vmcnt(55)
	v_mul_f32_e32 v26, v26, v27
	v_add_f32_e32 v29, 1.0, v29
	v_mul_f32_e32 v29, v28, v29
	ds_write_b32 v5, v26 offset:3584
	ds_write_b32 v5, v29 offset:28160
	ds_write_b32 v6, v30 offset:3584
	s_waitcnt vmcnt(50)
	v_mul_f32_e32 v34, v34, v35
	v_add_f32_e32 v37, 1.0, v37
	v_mul_f32_e32 v37, v36, v37
	ds_write_b32 v5, v34 offset:5376
	ds_write_b32 v5, v37 offset:29952
	ds_write_b32 v6, v38 offset:5376
	s_waitcnt vmcnt(45)
	v_mul_f32_e32 v42, v42, v43
	v_add_f32_e32 v45, 1.0, v45
	v_mul_f32_e32 v45, v44, v45
	ds_write_b32 v5, v42 offset:7168
	ds_write_b32 v5, v45 offset:31744
	ds_write_b32 v6, v46 offset:7168
	s_waitcnt vmcnt(40)
	v_mul_f32_e32 v50, v50, v51
	v_add_f32_e32 v53, 1.0, v53
	v_mul_f32_e32 v53, v52, v53
	ds_write_b32 v5, v50 offset:8960
	ds_write_b32 v5, v53 offset:33536
	ds_write_b32 v6, v54 offset:8960
	s_waitcnt vmcnt(35)
	v_mul_f32_e32 v58, v58, v59
	v_add_f32_e32 v61, 1.0, v61
	v_mul_f32_e32 v61, v60, v61
	ds_write_b32 v5, v58 offset:10752
	ds_write_b32 v5, v61 offset:35328
	ds_write_b32 v6, v62 offset:10752
	s_waitcnt vmcnt(30)
	v_mul_f32_e32 v66, v66, v67
	v_add_f32_e32 v69, 1.0, v69
	v_mul_f32_e32 v69, v68, v69
	ds_write_b32 v5, v66 offset:12544
	ds_write_b32 v5, v69 offset:37120
	ds_write_b32 v6, v70 offset:12544
	s_waitcnt vmcnt(25)
	v_mul_f32_e32 v74, v74, v75
	v_add_f32_e32 v77, 1.0, v77
	v_mul_f32_e32 v77, v76, v77
	ds_write_b32 v5, v74 offset:14336
	ds_write_b32 v5, v77 offset:38912
	ds_write_b32 v6, v78 offset:14336
	s_waitcnt vmcnt(20)
	v_mul_f32_e32 v82, v82, v83
	v_add_f32_e32 v85, 1.0, v85
	v_mul_f32_e32 v85, v84, v85
	ds_write_b32 v5, v82 offset:16128
	ds_write_b32 v5, v85 offset:40704
	ds_write_b32 v6, v86 offset:16128
	s_waitcnt vmcnt(15)
	v_mul_f32_e32 v90, v90, v91
	v_add_f32_e32 v93, 1.0, v93
	v_mul_f32_e32 v93, v92, v93
	ds_write_b32 v5, v90 offset:17920
	ds_write_b32 v5, v93 offset:42496
	ds_write_b32 v6, v94 offset:17920
	s_waitcnt vmcnt(10)
	v_mul_f32_e32 v98, v98, v99
	v_add_f32_e32 v101, 1.0, v101
	v_mul_f32_e32 v101, v100, v101
	ds_write_b32 v5, v98 offset:19712
	ds_write_b32 v5, v101 offset:44288
	ds_write_b32 v6, v102 offset:19712
	s_waitcnt vmcnt(5)
	v_mul_f32_e32 v106, v106, v107
	v_add_f32_e32 v109, 1.0, v109
	v_mul_f32_e32 v109, v108, v109
	ds_write_b32 v5, v106 offset:21504
	ds_write_b32 v5, v109 offset:46080
	ds_write_b32 v6, v110 offset:21504
	s_waitcnt vmcnt(0)
	v_cmp_gt_u32_e32 vcc, 0x140, v4
	s_and_saveexec_b64 s[68:69], vcc
	s_cbranch_execz .Ltb_p7_p13
	v_mul_f32_e32 v114, v114, v115
	v_add_f32_e32 v117, 1.0, v117
	v_mul_f32_e32 v117, v116, v117
	ds_write_b32 v5, v114 offset:23296
	ds_write_b32 v5, v117 offset:47872
	ds_write_b32 v6, v118 offset:23296
.Ltb_p7_p13:
	s_or_b64 exec, exec, s[68:69]
.LBB0_799:
	s_or_b64 exec, exec, s[68:69]
	s_mov_b64 s[36:37], 0
